# LRU pass2 step loop rewritten: fused-DPP (a,b) scan with DPP carry fold instead of log-domain prefix sums and bpermute broadcasts
# speedup vs baseline: 1.0418x; 1.0139x over previous
.LBB0_281:
	s_waitcnt lgkmcnt(0)
	v_mov_b64_e32 v[192:193], v[34:35]
	v_mov_b64_e32 v[194:195], v[32:33]
	v_mov_b64_e32 v[196:197], v[30:31]
	v_mov_b64_e32 v[198:199], v[28:29]
	v_mov_b64_e32 v[200:201], v[26:27]
	v_mov_b64_e32 v[202:203], v[24:25]
	v_mov_b64_e32 v[204:205], v[22:23]
	v_mov_b64_e32 v[206:207], v[20:21]
.Ll2_step:
	s_add_i32 s12, s14, 1
	s_cmp_lg_u32 s14, 7
	s_cselect_b32 s9, s12, 7
	s_sub_i32 s8, 7, s9
	s_cmp_lt_u32 s9, 4
	s_cselect_b32 s8, s9, s8
	s_cmp_gt_u32 s9, 3
	s_cselect_b32 s74, 0x2200000, 0
	s_ashr_i32 s9, s8, 31
	s_lshl_b64 s[16:17], s[8:9], 15
	s_lshl_b64 s[8:9], s[8:9], 14
	v_lshl_add_u64 v[84:85], v[52:53], 0, s[74:75]
	v_lshl_add_u64 v[86:87], v[54:55], 0, s[8:9]
	v_lshl_add_u64 v[84:85], v[84:85], 0, s[16:17]
	s_cmp_lt_u32 s14, 4
	s_cselect_b32 s8, s14, s11
	s_lshl_b32 s13, s8, 12
	v_add_u32_e32 v81, s13, v125
	s_waitcnt vmcnt(0)
	v_cvt_f32_f16_e32 v130, v2
	v_cvt_f32_f16_sdwa v146, v2 dst_sel:DWORD dst_unused:UNUSED_PAD src0_sel:WORD_1
	v_cvt_f32_f16_e32 v131, v3
	v_cvt_f32_f16_sdwa v147, v3 dst_sel:DWORD dst_unused:UNUSED_PAD src0_sel:WORD_1
	v_cvt_f32_f16_e32 v132, v4
	v_cvt_f32_f16_sdwa v148, v4 dst_sel:DWORD dst_unused:UNUSED_PAD src0_sel:WORD_1
	v_cvt_f32_f16_e32 v133, v5
	v_cvt_f32_f16_sdwa v149, v5 dst_sel:DWORD dst_unused:UNUSED_PAD src0_sel:WORD_1
	v_cvt_f32_f16_e32 v134, v6
	v_cvt_f32_f16_sdwa v150, v6 dst_sel:DWORD dst_unused:UNUSED_PAD src0_sel:WORD_1
	v_cvt_f32_f16_e32 v135, v7
	v_cvt_f32_f16_sdwa v151, v7 dst_sel:DWORD dst_unused:UNUSED_PAD src0_sel:WORD_1
	v_cvt_f32_f16_e32 v136, v8
	v_cvt_f32_f16_sdwa v152, v8 dst_sel:DWORD dst_unused:UNUSED_PAD src0_sel:WORD_1
	v_cvt_f32_f16_e32 v137, v9
	v_cvt_f32_f16_sdwa v153, v9 dst_sel:DWORD dst_unused:UNUSED_PAD src0_sel:WORD_1
	v_cvt_f32_f16_e32 v138, v10
	v_cvt_f32_f16_sdwa v154, v10 dst_sel:DWORD dst_unused:UNUSED_PAD src0_sel:WORD_1
	v_cvt_f32_f16_e32 v139, v11
	v_cvt_f32_f16_sdwa v155, v11 dst_sel:DWORD dst_unused:UNUSED_PAD src0_sel:WORD_1
	v_cvt_f32_f16_e32 v140, v12
	v_cvt_f32_f16_sdwa v156, v12 dst_sel:DWORD dst_unused:UNUSED_PAD src0_sel:WORD_1
	v_cvt_f32_f16_e32 v141, v13
	v_cvt_f32_f16_sdwa v157, v13 dst_sel:DWORD dst_unused:UNUSED_PAD src0_sel:WORD_1
	v_cvt_f32_f16_e32 v142, v14
	v_cvt_f32_f16_sdwa v158, v14 dst_sel:DWORD dst_unused:UNUSED_PAD src0_sel:WORD_1
	v_cvt_f32_f16_e32 v143, v15
	v_cvt_f32_f16_sdwa v159, v15 dst_sel:DWORD dst_unused:UNUSED_PAD src0_sel:WORD_1
	v_cvt_f32_f16_e32 v144, v16
	v_cvt_f32_f16_sdwa v160, v16 dst_sel:DWORD dst_unused:UNUSED_PAD src0_sel:WORD_1
	v_cvt_f32_f16_e32 v145, v17
	v_cvt_f32_f16_sdwa v161, v17 dst_sel:DWORD dst_unused:UNUSED_PAD src0_sel:WORD_1
	v_lshlrev_b32_e32 v162, 16, v56
	v_and_b32_e32 v163, 0xffff0000, v56
	v_lshlrev_b32_e32 v164, 16, v57
	v_and_b32_e32 v165, 0xffff0000, v57
	v_lshlrev_b32_e32 v166, 16, v58
	v_and_b32_e32 v167, 0xffff0000, v58
	v_lshlrev_b32_e32 v168, 16, v59
	v_and_b32_e32 v169, 0xffff0000, v59
	v_lshlrev_b32_e32 v170, 16, v60
	v_and_b32_e32 v171, 0xffff0000, v60
	v_lshlrev_b32_e32 v172, 16, v61
	v_and_b32_e32 v173, 0xffff0000, v61
	v_lshlrev_b32_e32 v174, 16, v62
	v_and_b32_e32 v175, 0xffff0000, v62
	v_lshlrev_b32_e32 v176, 16, v63
	v_and_b32_e32 v177, 0xffff0000, v63
	s_cmp_eq_u32 s14, 7
	s_cbranch_scc1 .Ll2_noload
	global_load_dwordx4 v[2:5], v[84:85], off
	global_load_dwordx4 v[6:9], v[84:85], off offset:1024
	global_load_dwordx4 v[10:13], v[84:85], off offset:2048
	global_load_dwordx4 v[14:17], v[84:85], off offset:3072
	global_load_dwordx2 v[56:57], v[86:87], off
	global_load_dwordx2 v[58:59], v[86:87], off offset:512
	global_load_dwordx2 v[60:61], v[86:87], off offset:1024
	global_load_dwordx2 v[62:63], v[86:87], off offset:1536
.Ll2_noload:
	v_exp_f32_e32 v130, v130
	v_exp_f32_e32 v131, v131
	v_exp_f32_e32 v132, v132
	v_exp_f32_e32 v133, v133
	v_exp_f32_e32 v134, v134
	v_exp_f32_e32 v135, v135
	v_exp_f32_e32 v136, v136
	v_exp_f32_e32 v137, v137
	v_exp_f32_e32 v138, v138
	v_exp_f32_e32 v139, v139
	v_exp_f32_e32 v140, v140
	v_exp_f32_e32 v141, v141
	v_exp_f32_e32 v142, v142
	v_exp_f32_e32 v143, v143
	v_exp_f32_e32 v144, v144
	v_exp_f32_e32 v145, v145
	s_cmp_gt_u32 s14, 3
	s_cbranch_scc1 .Ll2_bwd
	v_fmac_f32_dpp v146, v192, v130 row_shl:15 row_mask:0xf bank_mask:0xf bound_ctrl:1
	v_fmac_f32_dpp v147, v193, v131 row_shl:15 row_mask:0xf bank_mask:0xf bound_ctrl:1
	v_fmac_f32_dpp v148, v194, v132 row_shl:15 row_mask:0xf bank_mask:0xf bound_ctrl:1
	v_fmac_f32_dpp v149, v195, v133 row_shl:15 row_mask:0xf bank_mask:0xf bound_ctrl:1
	v_fmac_f32_dpp v150, v196, v134 row_shl:15 row_mask:0xf bank_mask:0xf bound_ctrl:1
	v_fmac_f32_dpp v151, v197, v135 row_shl:15 row_mask:0xf bank_mask:0xf bound_ctrl:1
	v_fmac_f32_dpp v152, v198, v136 row_shl:15 row_mask:0xf bank_mask:0xf bound_ctrl:1
	v_fmac_f32_dpp v153, v199, v137 row_shl:15 row_mask:0xf bank_mask:0xf bound_ctrl:1
	v_fmac_f32_dpp v154, v200, v138 row_shl:15 row_mask:0xf bank_mask:0xf bound_ctrl:1
	v_fmac_f32_dpp v155, v201, v139 row_shl:15 row_mask:0xf bank_mask:0xf bound_ctrl:1
	v_fmac_f32_dpp v156, v202, v140 row_shl:15 row_mask:0xf bank_mask:0xf bound_ctrl:1
	v_fmac_f32_dpp v157, v203, v141 row_shl:15 row_mask:0xf bank_mask:0xf bound_ctrl:1
	v_fmac_f32_dpp v158, v204, v142 row_shl:15 row_mask:0xf bank_mask:0xf bound_ctrl:1
	v_fmac_f32_dpp v159, v205, v143 row_shl:15 row_mask:0xf bank_mask:0xf bound_ctrl:1
	v_fmac_f32_dpp v160, v206, v144 row_shl:15 row_mask:0xf bank_mask:0xf bound_ctrl:1
	v_fmac_f32_dpp v161, v207, v145 row_shl:15 row_mask:0xf bank_mask:0xf bound_ctrl:1
	v_fmac_f32_dpp v146, v146, v130 row_shr:1 row_mask:0xf bank_mask:0xf bound_ctrl:1
	v_mul_f32_dpp v130, v130, v130 row_shr:1 row_mask:0xf bank_mask:0xf
	v_fmac_f32_dpp v147, v147, v131 row_shr:1 row_mask:0xf bank_mask:0xf bound_ctrl:1
	v_mul_f32_dpp v131, v131, v131 row_shr:1 row_mask:0xf bank_mask:0xf
	v_fmac_f32_dpp v148, v148, v132 row_shr:1 row_mask:0xf bank_mask:0xf bound_ctrl:1
	v_mul_f32_dpp v132, v132, v132 row_shr:1 row_mask:0xf bank_mask:0xf
	v_fmac_f32_dpp v149, v149, v133 row_shr:1 row_mask:0xf bank_mask:0xf bound_ctrl:1
	v_mul_f32_dpp v133, v133, v133 row_shr:1 row_mask:0xf bank_mask:0xf
	v_fmac_f32_dpp v150, v150, v134 row_shr:1 row_mask:0xf bank_mask:0xf bound_ctrl:1
	v_mul_f32_dpp v134, v134, v134 row_shr:1 row_mask:0xf bank_mask:0xf
	v_fmac_f32_dpp v151, v151, v135 row_shr:1 row_mask:0xf bank_mask:0xf bound_ctrl:1
	v_mul_f32_dpp v135, v135, v135 row_shr:1 row_mask:0xf bank_mask:0xf
	v_fmac_f32_dpp v152, v152, v136 row_shr:1 row_mask:0xf bank_mask:0xf bound_ctrl:1
	v_mul_f32_dpp v136, v136, v136 row_shr:1 row_mask:0xf bank_mask:0xf
	v_fmac_f32_dpp v153, v153, v137 row_shr:1 row_mask:0xf bank_mask:0xf bound_ctrl:1
	v_mul_f32_dpp v137, v137, v137 row_shr:1 row_mask:0xf bank_mask:0xf
	v_fmac_f32_dpp v154, v154, v138 row_shr:1 row_mask:0xf bank_mask:0xf bound_ctrl:1
	v_mul_f32_dpp v138, v138, v138 row_shr:1 row_mask:0xf bank_mask:0xf
	v_fmac_f32_dpp v155, v155, v139 row_shr:1 row_mask:0xf bank_mask:0xf bound_ctrl:1
	v_mul_f32_dpp v139, v139, v139 row_shr:1 row_mask:0xf bank_mask:0xf
	v_fmac_f32_dpp v156, v156, v140 row_shr:1 row_mask:0xf bank_mask:0xf bound_ctrl:1
	v_mul_f32_dpp v140, v140, v140 row_shr:1 row_mask:0xf bank_mask:0xf
	v_fmac_f32_dpp v157, v157, v141 row_shr:1 row_mask:0xf bank_mask:0xf bound_ctrl:1
	v_mul_f32_dpp v141, v141, v141 row_shr:1 row_mask:0xf bank_mask:0xf
	v_fmac_f32_dpp v158, v158, v142 row_shr:1 row_mask:0xf bank_mask:0xf bound_ctrl:1
	v_mul_f32_dpp v142, v142, v142 row_shr:1 row_mask:0xf bank_mask:0xf
	v_fmac_f32_dpp v159, v159, v143 row_shr:1 row_mask:0xf bank_mask:0xf bound_ctrl:1
	v_mul_f32_dpp v143, v143, v143 row_shr:1 row_mask:0xf bank_mask:0xf
	v_fmac_f32_dpp v160, v160, v144 row_shr:1 row_mask:0xf bank_mask:0xf bound_ctrl:1
	v_mul_f32_dpp v144, v144, v144 row_shr:1 row_mask:0xf bank_mask:0xf
	v_fmac_f32_dpp v161, v161, v145 row_shr:1 row_mask:0xf bank_mask:0xf bound_ctrl:1
	v_mul_f32_dpp v145, v145, v145 row_shr:1 row_mask:0xf bank_mask:0xf
	v_fmac_f32_dpp v146, v146, v130 row_shr:2 row_mask:0xf bank_mask:0xf bound_ctrl:1
	v_mul_f32_dpp v130, v130, v130 row_shr:2 row_mask:0xf bank_mask:0xf
	v_fmac_f32_dpp v147, v147, v131 row_shr:2 row_mask:0xf bank_mask:0xf bound_ctrl:1
	v_mul_f32_dpp v131, v131, v131 row_shr:2 row_mask:0xf bank_mask:0xf
	v_fmac_f32_dpp v148, v148, v132 row_shr:2 row_mask:0xf bank_mask:0xf bound_ctrl:1
	v_mul_f32_dpp v132, v132, v132 row_shr:2 row_mask:0xf bank_mask:0xf
	v_fmac_f32_dpp v149, v149, v133 row_shr:2 row_mask:0xf bank_mask:0xf bound_ctrl:1
	v_mul_f32_dpp v133, v133, v133 row_shr:2 row_mask:0xf bank_mask:0xf
	v_fmac_f32_dpp v150, v150, v134 row_shr:2 row_mask:0xf bank_mask:0xf bound_ctrl:1
	v_mul_f32_dpp v134, v134, v134 row_shr:2 row_mask:0xf bank_mask:0xf
	v_fmac_f32_dpp v151, v151, v135 row_shr:2 row_mask:0xf bank_mask:0xf bound_ctrl:1
	v_mul_f32_dpp v135, v135, v135 row_shr:2 row_mask:0xf bank_mask:0xf
	v_fmac_f32_dpp v152, v152, v136 row_shr:2 row_mask:0xf bank_mask:0xf bound_ctrl:1
	v_mul_f32_dpp v136, v136, v136 row_shr:2 row_mask:0xf bank_mask:0xf
	v_fmac_f32_dpp v153, v153, v137 row_shr:2 row_mask:0xf bank_mask:0xf bound_ctrl:1
	v_mul_f32_dpp v137, v137, v137 row_shr:2 row_mask:0xf bank_mask:0xf
	v_fmac_f32_dpp v154, v154, v138 row_shr:2 row_mask:0xf bank_mask:0xf bound_ctrl:1
	v_mul_f32_dpp v138, v138, v138 row_shr:2 row_mask:0xf bank_mask:0xf
	v_fmac_f32_dpp v155, v155, v139 row_shr:2 row_mask:0xf bank_mask:0xf bound_ctrl:1
	v_mul_f32_dpp v139, v139, v139 row_shr:2 row_mask:0xf bank_mask:0xf
	v_fmac_f32_dpp v156, v156, v140 row_shr:2 row_mask:0xf bank_mask:0xf bound_ctrl:1
	v_mul_f32_dpp v140, v140, v140 row_shr:2 row_mask:0xf bank_mask:0xf
	v_fmac_f32_dpp v157, v157, v141 row_shr:2 row_mask:0xf bank_mask:0xf bound_ctrl:1
	v_mul_f32_dpp v141, v141, v141 row_shr:2 row_mask:0xf bank_mask:0xf
	v_fmac_f32_dpp v158, v158, v142 row_shr:2 row_mask:0xf bank_mask:0xf bound_ctrl:1
	v_mul_f32_dpp v142, v142, v142 row_shr:2 row_mask:0xf bank_mask:0xf
	v_fmac_f32_dpp v159, v159, v143 row_shr:2 row_mask:0xf bank_mask:0xf bound_ctrl:1
	v_mul_f32_dpp v143, v143, v143 row_shr:2 row_mask:0xf bank_mask:0xf
	v_fmac_f32_dpp v160, v160, v144 row_shr:2 row_mask:0xf bank_mask:0xf bound_ctrl:1
	v_mul_f32_dpp v144, v144, v144 row_shr:2 row_mask:0xf bank_mask:0xf
	v_fmac_f32_dpp v161, v161, v145 row_shr:2 row_mask:0xf bank_mask:0xf bound_ctrl:1
	v_mul_f32_dpp v145, v145, v145 row_shr:2 row_mask:0xf bank_mask:0xf
	v_fmac_f32_dpp v146, v146, v130 row_shr:4 row_mask:0xf bank_mask:0xf bound_ctrl:1
	v_mul_f32_dpp v130, v130, v130 row_shr:4 row_mask:0xf bank_mask:0xf
	v_fmac_f32_dpp v147, v147, v131 row_shr:4 row_mask:0xf bank_mask:0xf bound_ctrl:1
	v_mul_f32_dpp v131, v131, v131 row_shr:4 row_mask:0xf bank_mask:0xf
	v_fmac_f32_dpp v148, v148, v132 row_shr:4 row_mask:0xf bank_mask:0xf bound_ctrl:1
	v_mul_f32_dpp v132, v132, v132 row_shr:4 row_mask:0xf bank_mask:0xf
	v_fmac_f32_dpp v149, v149, v133 row_shr:4 row_mask:0xf bank_mask:0xf bound_ctrl:1
	v_mul_f32_dpp v133, v133, v133 row_shr:4 row_mask:0xf bank_mask:0xf
	v_fmac_f32_dpp v150, v150, v134 row_shr:4 row_mask:0xf bank_mask:0xf bound_ctrl:1
	v_mul_f32_dpp v134, v134, v134 row_shr:4 row_mask:0xf bank_mask:0xf
	v_fmac_f32_dpp v151, v151, v135 row_shr:4 row_mask:0xf bank_mask:0xf bound_ctrl:1
	v_mul_f32_dpp v135, v135, v135 row_shr:4 row_mask:0xf bank_mask:0xf
	v_fmac_f32_dpp v152, v152, v136 row_shr:4 row_mask:0xf bank_mask:0xf bound_ctrl:1
	v_mul_f32_dpp v136, v136, v136 row_shr:4 row_mask:0xf bank_mask:0xf
	v_fmac_f32_dpp v153, v153, v137 row_shr:4 row_mask:0xf bank_mask:0xf bound_ctrl:1
	v_mul_f32_dpp v137, v137, v137 row_shr:4 row_mask:0xf bank_mask:0xf
	v_fmac_f32_dpp v154, v154, v138 row_shr:4 row_mask:0xf bank_mask:0xf bound_ctrl:1
	v_mul_f32_dpp v138, v138, v138 row_shr:4 row_mask:0xf bank_mask:0xf
	v_fmac_f32_dpp v155, v155, v139 row_shr:4 row_mask:0xf bank_mask:0xf bound_ctrl:1
	v_mul_f32_dpp v139, v139, v139 row_shr:4 row_mask:0xf bank_mask:0xf
	v_fmac_f32_dpp v156, v156, v140 row_shr:4 row_mask:0xf bank_mask:0xf bound_ctrl:1
	v_mul_f32_dpp v140, v140, v140 row_shr:4 row_mask:0xf bank_mask:0xf
	v_fmac_f32_dpp v157, v157, v141 row_shr:4 row_mask:0xf bank_mask:0xf bound_ctrl:1
	v_mul_f32_dpp v141, v141, v141 row_shr:4 row_mask:0xf bank_mask:0xf
	v_fmac_f32_dpp v158, v158, v142 row_shr:4 row_mask:0xf bank_mask:0xf bound_ctrl:1
	v_mul_f32_dpp v142, v142, v142 row_shr:4 row_mask:0xf bank_mask:0xf
	v_fmac_f32_dpp v159, v159, v143 row_shr:4 row_mask:0xf bank_mask:0xf bound_ctrl:1
	v_mul_f32_dpp v143, v143, v143 row_shr:4 row_mask:0xf bank_mask:0xf
	v_fmac_f32_dpp v160, v160, v144 row_shr:4 row_mask:0xf bank_mask:0xf bound_ctrl:1
	v_mul_f32_dpp v144, v144, v144 row_shr:4 row_mask:0xf bank_mask:0xf
	v_fmac_f32_dpp v161, v161, v145 row_shr:4 row_mask:0xf bank_mask:0xf bound_ctrl:1
	v_mul_f32_dpp v145, v145, v145 row_shr:4 row_mask:0xf bank_mask:0xf
	v_fmac_f32_dpp v146, v146, v130 row_shr:8 row_mask:0xf bank_mask:0xf bound_ctrl:1
	v_fmac_f32_dpp v147, v147, v131 row_shr:8 row_mask:0xf bank_mask:0xf bound_ctrl:1
	v_fmac_f32_dpp v148, v148, v132 row_shr:8 row_mask:0xf bank_mask:0xf bound_ctrl:1
	v_fmac_f32_dpp v149, v149, v133 row_shr:8 row_mask:0xf bank_mask:0xf bound_ctrl:1
	v_fmac_f32_dpp v150, v150, v134 row_shr:8 row_mask:0xf bank_mask:0xf bound_ctrl:1
	v_fmac_f32_dpp v151, v151, v135 row_shr:8 row_mask:0xf bank_mask:0xf bound_ctrl:1
	v_fmac_f32_dpp v152, v152, v136 row_shr:8 row_mask:0xf bank_mask:0xf bound_ctrl:1
	v_fmac_f32_dpp v153, v153, v137 row_shr:8 row_mask:0xf bank_mask:0xf bound_ctrl:1
	v_fmac_f32_dpp v154, v154, v138 row_shr:8 row_mask:0xf bank_mask:0xf bound_ctrl:1
	v_fmac_f32_dpp v155, v155, v139 row_shr:8 row_mask:0xf bank_mask:0xf bound_ctrl:1
	v_fmac_f32_dpp v156, v156, v140 row_shr:8 row_mask:0xf bank_mask:0xf bound_ctrl:1
	v_fmac_f32_dpp v157, v157, v141 row_shr:8 row_mask:0xf bank_mask:0xf bound_ctrl:1
	v_fmac_f32_dpp v158, v158, v142 row_shr:8 row_mask:0xf bank_mask:0xf bound_ctrl:1
	v_fmac_f32_dpp v159, v159, v143 row_shr:8 row_mask:0xf bank_mask:0xf bound_ctrl:1
	v_fmac_f32_dpp v160, v160, v144 row_shr:8 row_mask:0xf bank_mask:0xf bound_ctrl:1
	v_fmac_f32_dpp v161, v161, v145 row_shr:8 row_mask:0xf bank_mask:0xf bound_ctrl:1
	ds_write2st64_b32 v81, v146, v147 offset0:16 offset1:17
	ds_write2st64_b32 v81, v148, v149 offset0:18 offset1:19
	ds_write2st64_b32 v81, v150, v151 offset0:20 offset1:21
	ds_write2st64_b32 v81, v152, v153 offset0:22 offset1:23
	ds_write2st64_b32 v81, v154, v155 offset0:24 offset1:25
	ds_write2st64_b32 v81, v156, v157 offset0:26 offset1:27
	ds_write2st64_b32 v81, v158, v159 offset0:28 offset1:29
	ds_write2st64_b32 v81, v160, v161 offset0:30 offset1:31
	v_mov_b64_e32 v[192:193], v[146:147]
	v_mov_b64_e32 v[194:195], v[148:149]
	v_mov_b64_e32 v[196:197], v[150:151]
	v_mov_b64_e32 v[198:199], v[152:153]
	v_mov_b64_e32 v[200:201], v[154:155]
	v_mov_b64_e32 v[202:203], v[156:157]
	v_mov_b64_e32 v[204:205], v[158:159]
	v_mov_b64_e32 v[206:207], v[160:161]
	s_branch .Ll2_tail
.Ll2_bwd:
	ds_read2st64_b32 v[64:65], v81 offset0:16 offset1:17
	ds_read2st64_b32 v[66:67], v81 offset0:18 offset1:19
	ds_read2st64_b32 v[68:69], v81 offset0:20 offset1:21
	ds_read2st64_b32 v[70:71], v81 offset0:22 offset1:23
	ds_read2st64_b32 v[72:73], v81 offset0:24 offset1:25
	ds_read2st64_b32 v[74:75], v81 offset0:26 offset1:27
	ds_read2st64_b32 v[76:77], v81 offset0:28 offset1:29
	ds_read2st64_b32 v[78:79], v81 offset0:30 offset1:31
	s_cmp_lg_u32 s14, 4
	s_cbranch_scc1 .Ll2_bwd_go
	v_mov_b64_e32 v[192:193], v[36:37]
	v_mov_b64_e32 v[194:195], v[38:39]
	v_mov_b64_e32 v[196:197], v[40:41]
	v_mov_b64_e32 v[198:199], v[42:43]
	v_mov_b64_e32 v[200:201], v[44:45]
	v_mov_b64_e32 v[202:203], v[46:47]
	v_mov_b64_e32 v[204:205], v[48:49]
	v_mov_b64_e32 v[206:207], v[50:51]
	s_nop 1
.Ll2_bwd_go:
	v_fmac_f32_dpp v146, v192, v130 row_shr:15 row_mask:0xf bank_mask:0xf bound_ctrl:1
	v_fmac_f32_dpp v147, v193, v131 row_shr:15 row_mask:0xf bank_mask:0xf bound_ctrl:1
	v_fmac_f32_dpp v148, v194, v132 row_shr:15 row_mask:0xf bank_mask:0xf bound_ctrl:1
	v_fmac_f32_dpp v149, v195, v133 row_shr:15 row_mask:0xf bank_mask:0xf bound_ctrl:1
	v_fmac_f32_dpp v150, v196, v134 row_shr:15 row_mask:0xf bank_mask:0xf bound_ctrl:1
	v_fmac_f32_dpp v151, v197, v135 row_shr:15 row_mask:0xf bank_mask:0xf bound_ctrl:1
	v_fmac_f32_dpp v152, v198, v136 row_shr:15 row_mask:0xf bank_mask:0xf bound_ctrl:1
	v_fmac_f32_dpp v153, v199, v137 row_shr:15 row_mask:0xf bank_mask:0xf bound_ctrl:1
	v_fmac_f32_dpp v154, v200, v138 row_shr:15 row_mask:0xf bank_mask:0xf bound_ctrl:1
	v_fmac_f32_dpp v155, v201, v139 row_shr:15 row_mask:0xf bank_mask:0xf bound_ctrl:1
	v_fmac_f32_dpp v156, v202, v140 row_shr:15 row_mask:0xf bank_mask:0xf bound_ctrl:1
	v_fmac_f32_dpp v157, v203, v141 row_shr:15 row_mask:0xf bank_mask:0xf bound_ctrl:1
	v_fmac_f32_dpp v158, v204, v142 row_shr:15 row_mask:0xf bank_mask:0xf bound_ctrl:1
	v_fmac_f32_dpp v159, v205, v143 row_shr:15 row_mask:0xf bank_mask:0xf bound_ctrl:1
	v_fmac_f32_dpp v160, v206, v144 row_shr:15 row_mask:0xf bank_mask:0xf bound_ctrl:1
	v_fmac_f32_dpp v161, v207, v145 row_shr:15 row_mask:0xf bank_mask:0xf bound_ctrl:1
	v_fmac_f32_dpp v146, v146, v130 row_shl:1 row_mask:0xf bank_mask:0xf bound_ctrl:1
	v_mul_f32_dpp v130, v130, v130 row_shl:1 row_mask:0xf bank_mask:0xf
	v_fmac_f32_dpp v147, v147, v131 row_shl:1 row_mask:0xf bank_mask:0xf bound_ctrl:1
	v_mul_f32_dpp v131, v131, v131 row_shl:1 row_mask:0xf bank_mask:0xf
	v_fmac_f32_dpp v148, v148, v132 row_shl:1 row_mask:0xf bank_mask:0xf bound_ctrl:1
	v_mul_f32_dpp v132, v132, v132 row_shl:1 row_mask:0xf bank_mask:0xf
	v_fmac_f32_dpp v149, v149, v133 row_shl:1 row_mask:0xf bank_mask:0xf bound_ctrl:1
	v_mul_f32_dpp v133, v133, v133 row_shl:1 row_mask:0xf bank_mask:0xf
	v_fmac_f32_dpp v150, v150, v134 row_shl:1 row_mask:0xf bank_mask:0xf bound_ctrl:1
	v_mul_f32_dpp v134, v134, v134 row_shl:1 row_mask:0xf bank_mask:0xf
	v_fmac_f32_dpp v151, v151, v135 row_shl:1 row_mask:0xf bank_mask:0xf bound_ctrl:1
	v_mul_f32_dpp v135, v135, v135 row_shl:1 row_mask:0xf bank_mask:0xf
	v_fmac_f32_dpp v152, v152, v136 row_shl:1 row_mask:0xf bank_mask:0xf bound_ctrl:1
	v_mul_f32_dpp v136, v136, v136 row_shl:1 row_mask:0xf bank_mask:0xf
	v_fmac_f32_dpp v153, v153, v137 row_shl:1 row_mask:0xf bank_mask:0xf bound_ctrl:1
	v_mul_f32_dpp v137, v137, v137 row_shl:1 row_mask:0xf bank_mask:0xf
	v_fmac_f32_dpp v154, v154, v138 row_shl:1 row_mask:0xf bank_mask:0xf bound_ctrl:1
	v_mul_f32_dpp v138, v138, v138 row_shl:1 row_mask:0xf bank_mask:0xf
	v_fmac_f32_dpp v155, v155, v139 row_shl:1 row_mask:0xf bank_mask:0xf bound_ctrl:1
	v_mul_f32_dpp v139, v139, v139 row_shl:1 row_mask:0xf bank_mask:0xf
	v_fmac_f32_dpp v156, v156, v140 row_shl:1 row_mask:0xf bank_mask:0xf bound_ctrl:1
	v_mul_f32_dpp v140, v140, v140 row_shl:1 row_mask:0xf bank_mask:0xf
	v_fmac_f32_dpp v157, v157, v141 row_shl:1 row_mask:0xf bank_mask:0xf bound_ctrl:1
	v_mul_f32_dpp v141, v141, v141 row_shl:1 row_mask:0xf bank_mask:0xf
	v_fmac_f32_dpp v158, v158, v142 row_shl:1 row_mask:0xf bank_mask:0xf bound_ctrl:1
	v_mul_f32_dpp v142, v142, v142 row_shl:1 row_mask:0xf bank_mask:0xf
	v_fmac_f32_dpp v159, v159, v143 row_shl:1 row_mask:0xf bank_mask:0xf bound_ctrl:1
	v_mul_f32_dpp v143, v143, v143 row_shl:1 row_mask:0xf bank_mask:0xf
	v_fmac_f32_dpp v160, v160, v144 row_shl:1 row_mask:0xf bank_mask:0xf bound_ctrl:1
	v_mul_f32_dpp v144, v144, v144 row_shl:1 row_mask:0xf bank_mask:0xf
	v_fmac_f32_dpp v161, v161, v145 row_shl:1 row_mask:0xf bank_mask:0xf bound_ctrl:1
	v_mul_f32_dpp v145, v145, v145 row_shl:1 row_mask:0xf bank_mask:0xf
	v_fmac_f32_dpp v146, v146, v130 row_shl:2 row_mask:0xf bank_mask:0xf bound_ctrl:1
	v_mul_f32_dpp v130, v130, v130 row_shl:2 row_mask:0xf bank_mask:0xf
	v_fmac_f32_dpp v147, v147, v131 row_shl:2 row_mask:0xf bank_mask:0xf bound_ctrl:1
	v_mul_f32_dpp v131, v131, v131 row_shl:2 row_mask:0xf bank_mask:0xf
	v_fmac_f32_dpp v148, v148, v132 row_shl:2 row_mask:0xf bank_mask:0xf bound_ctrl:1
	v_mul_f32_dpp v132, v132, v132 row_shl:2 row_mask:0xf bank_mask:0xf
	v_fmac_f32_dpp v149, v149, v133 row_shl:2 row_mask:0xf bank_mask:0xf bound_ctrl:1
	v_mul_f32_dpp v133, v133, v133 row_shl:2 row_mask:0xf bank_mask:0xf
	v_fmac_f32_dpp v150, v150, v134 row_shl:2 row_mask:0xf bank_mask:0xf bound_ctrl:1
	v_mul_f32_dpp v134, v134, v134 row_shl:2 row_mask:0xf bank_mask:0xf
	v_fmac_f32_dpp v151, v151, v135 row_shl:2 row_mask:0xf bank_mask:0xf bound_ctrl:1
	v_mul_f32_dpp v135, v135, v135 row_shl:2 row_mask:0xf bank_mask:0xf
	v_fmac_f32_dpp v152, v152, v136 row_shl:2 row_mask:0xf bank_mask:0xf bound_ctrl:1
	v_mul_f32_dpp v136, v136, v136 row_shl:2 row_mask:0xf bank_mask:0xf
	v_fmac_f32_dpp v153, v153, v137 row_shl:2 row_mask:0xf bank_mask:0xf bound_ctrl:1
	v_mul_f32_dpp v137, v137, v137 row_shl:2 row_mask:0xf bank_mask:0xf
	v_fmac_f32_dpp v154, v154, v138 row_shl:2 row_mask:0xf bank_mask:0xf bound_ctrl:1
	v_mul_f32_dpp v138, v138, v138 row_shl:2 row_mask:0xf bank_mask:0xf
	v_fmac_f32_dpp v155, v155, v139 row_shl:2 row_mask:0xf bank_mask:0xf bound_ctrl:1
	v_mul_f32_dpp v139, v139, v139 row_shl:2 row_mask:0xf bank_mask:0xf
	v_fmac_f32_dpp v156, v156, v140 row_shl:2 row_mask:0xf bank_mask:0xf bound_ctrl:1
	v_mul_f32_dpp v140, v140, v140 row_shl:2 row_mask:0xf bank_mask:0xf
	v_fmac_f32_dpp v157, v157, v141 row_shl:2 row_mask:0xf bank_mask:0xf bound_ctrl:1
	v_mul_f32_dpp v141, v141, v141 row_shl:2 row_mask:0xf bank_mask:0xf
	v_fmac_f32_dpp v158, v158, v142 row_shl:2 row_mask:0xf bank_mask:0xf bound_ctrl:1
	v_mul_f32_dpp v142, v142, v142 row_shl:2 row_mask:0xf bank_mask:0xf
	v_fmac_f32_dpp v159, v159, v143 row_shl:2 row_mask:0xf bank_mask:0xf bound_ctrl:1
	v_mul_f32_dpp v143, v143, v143 row_shl:2 row_mask:0xf bank_mask:0xf
	v_fmac_f32_dpp v160, v160, v144 row_shl:2 row_mask:0xf bank_mask:0xf bound_ctrl:1
	v_mul_f32_dpp v144, v144, v144 row_shl:2 row_mask:0xf bank_mask:0xf
	v_fmac_f32_dpp v161, v161, v145 row_shl:2 row_mask:0xf bank_mask:0xf bound_ctrl:1
	v_mul_f32_dpp v145, v145, v145 row_shl:2 row_mask:0xf bank_mask:0xf
	v_fmac_f32_dpp v146, v146, v130 row_shl:4 row_mask:0xf bank_mask:0xf bound_ctrl:1
	v_mul_f32_dpp v130, v130, v130 row_shl:4 row_mask:0xf bank_mask:0xf
	v_fmac_f32_dpp v147, v147, v131 row_shl:4 row_mask:0xf bank_mask:0xf bound_ctrl:1
	v_mul_f32_dpp v131, v131, v131 row_shl:4 row_mask:0xf bank_mask:0xf
	v_fmac_f32_dpp v148, v148, v132 row_shl:4 row_mask:0xf bank_mask:0xf bound_ctrl:1
	v_mul_f32_dpp v132, v132, v132 row_shl:4 row_mask:0xf bank_mask:0xf
	v_fmac_f32_dpp v149, v149, v133 row_shl:4 row_mask:0xf bank_mask:0xf bound_ctrl:1
	v_mul_f32_dpp v133, v133, v133 row_shl:4 row_mask:0xf bank_mask:0xf
	v_fmac_f32_dpp v150, v150, v134 row_shl:4 row_mask:0xf bank_mask:0xf bound_ctrl:1
	v_mul_f32_dpp v134, v134, v134 row_shl:4 row_mask:0xf bank_mask:0xf
	v_fmac_f32_dpp v151, v151, v135 row_shl:4 row_mask:0xf bank_mask:0xf bound_ctrl:1
	v_mul_f32_dpp v135, v135, v135 row_shl:4 row_mask:0xf bank_mask:0xf
	v_fmac_f32_dpp v152, v152, v136 row_shl:4 row_mask:0xf bank_mask:0xf bound_ctrl:1
	v_mul_f32_dpp v136, v136, v136 row_shl:4 row_mask:0xf bank_mask:0xf
	v_fmac_f32_dpp v153, v153, v137 row_shl:4 row_mask:0xf bank_mask:0xf bound_ctrl:1
	v_mul_f32_dpp v137, v137, v137 row_shl:4 row_mask:0xf bank_mask:0xf
	v_fmac_f32_dpp v154, v154, v138 row_shl:4 row_mask:0xf bank_mask:0xf bound_ctrl:1
	v_mul_f32_dpp v138, v138, v138 row_shl:4 row_mask:0xf bank_mask:0xf
	v_fmac_f32_dpp v155, v155, v139 row_shl:4 row_mask:0xf bank_mask:0xf bound_ctrl:1
	v_mul_f32_dpp v139, v139, v139 row_shl:4 row_mask:0xf bank_mask:0xf
	v_fmac_f32_dpp v156, v156, v140 row_shl:4 row_mask:0xf bank_mask:0xf bound_ctrl:1
	v_mul_f32_dpp v140, v140, v140 row_shl:4 row_mask:0xf bank_mask:0xf
	v_fmac_f32_dpp v157, v157, v141 row_shl:4 row_mask:0xf bank_mask:0xf bound_ctrl:1
	v_mul_f32_dpp v141, v141, v141 row_shl:4 row_mask:0xf bank_mask:0xf
	v_fmac_f32_dpp v158, v158, v142 row_shl:4 row_mask:0xf bank_mask:0xf bound_ctrl:1
	v_mul_f32_dpp v142, v142, v142 row_shl:4 row_mask:0xf bank_mask:0xf
	v_fmac_f32_dpp v159, v159, v143 row_shl:4 row_mask:0xf bank_mask:0xf bound_ctrl:1
	v_mul_f32_dpp v143, v143, v143 row_shl:4 row_mask:0xf bank_mask:0xf
	v_fmac_f32_dpp v160, v160, v144 row_shl:4 row_mask:0xf bank_mask:0xf bound_ctrl:1
	v_mul_f32_dpp v144, v144, v144 row_shl:4 row_mask:0xf bank_mask:0xf
	v_fmac_f32_dpp v161, v161, v145 row_shl:4 row_mask:0xf bank_mask:0xf bound_ctrl:1
	v_mul_f32_dpp v145, v145, v145 row_shl:4 row_mask:0xf bank_mask:0xf
	v_fmac_f32_dpp v146, v146, v130 row_shl:8 row_mask:0xf bank_mask:0xf bound_ctrl:1
	v_fmac_f32_dpp v147, v147, v131 row_shl:8 row_mask:0xf bank_mask:0xf bound_ctrl:1
	v_fmac_f32_dpp v148, v148, v132 row_shl:8 row_mask:0xf bank_mask:0xf bound_ctrl:1
	v_fmac_f32_dpp v149, v149, v133 row_shl:8 row_mask:0xf bank_mask:0xf bound_ctrl:1
	v_fmac_f32_dpp v150, v150, v134 row_shl:8 row_mask:0xf bank_mask:0xf bound_ctrl:1
	v_fmac_f32_dpp v151, v151, v135 row_shl:8 row_mask:0xf bank_mask:0xf bound_ctrl:1
	v_fmac_f32_dpp v152, v152, v136 row_shl:8 row_mask:0xf bank_mask:0xf bound_ctrl:1
	v_fmac_f32_dpp v153, v153, v137 row_shl:8 row_mask:0xf bank_mask:0xf bound_ctrl:1
	v_fmac_f32_dpp v154, v154, v138 row_shl:8 row_mask:0xf bank_mask:0xf bound_ctrl:1
	v_fmac_f32_dpp v155, v155, v139 row_shl:8 row_mask:0xf bank_mask:0xf bound_ctrl:1
	v_fmac_f32_dpp v156, v156, v140 row_shl:8 row_mask:0xf bank_mask:0xf bound_ctrl:1
	v_fmac_f32_dpp v157, v157, v141 row_shl:8 row_mask:0xf bank_mask:0xf bound_ctrl:1
	v_fmac_f32_dpp v158, v158, v142 row_shl:8 row_mask:0xf bank_mask:0xf bound_ctrl:1
	v_fmac_f32_dpp v159, v159, v143 row_shl:8 row_mask:0xf bank_mask:0xf bound_ctrl:1
	v_fmac_f32_dpp v160, v160, v144 row_shl:8 row_mask:0xf bank_mask:0xf bound_ctrl:1
	v_fmac_f32_dpp v161, v161, v145 row_shl:8 row_mask:0xf bank_mask:0xf bound_ctrl:1
	v_mov_b64_e32 v[192:193], v[146:147]
	v_mov_b64_e32 v[194:195], v[148:149]
	v_mov_b64_e32 v[196:197], v[150:151]
	v_mov_b64_e32 v[198:199], v[152:153]
	v_mov_b64_e32 v[200:201], v[154:155]
	v_mov_b64_e32 v[202:203], v[156:157]
	v_mov_b64_e32 v[204:205], v[158:159]
	v_mov_b64_e32 v[206:207], v[160:161]
	s_waitcnt lgkmcnt(0)
	v_add_f32_e32 v64, v64, v146
	v_add_f32_e32 v65, v65, v147
	v_add_f32_e32 v66, v66, v148
	v_add_f32_e32 v67, v67, v149
	v_add_f32_e32 v68, v68, v150
	v_add_f32_e32 v69, v69, v151
	v_add_f32_e32 v70, v70, v152
	v_add_f32_e32 v71, v71, v153
	v_add_f32_e32 v72, v72, v154
	v_add_f32_e32 v73, v73, v155
	v_add_f32_e32 v74, v74, v156
	v_add_f32_e32 v75, v75, v157
	v_add_f32_e32 v76, v76, v158
	v_add_f32_e32 v77, v77, v159
	v_add_f32_e32 v78, v78, v160
	v_add_f32_e32 v79, v79, v161
	v_mul_f32_e32 v64, v64, v162
	v_mul_f32_e32 v65, v65, v163
	v_mul_f32_e32 v66, v66, v164
	v_mul_f32_e32 v67, v67, v165
	v_mul_f32_e32 v68, v68, v166
	v_mul_f32_e32 v69, v69, v167
	v_mul_f32_e32 v70, v70, v168
	v_mul_f32_e32 v71, v71, v169
	v_mul_f32_e32 v72, v72, v170
	v_mul_f32_e32 v73, v73, v171
	v_mul_f32_e32 v74, v74, v172
	v_mul_f32_e32 v75, v75, v173
	v_mul_f32_e32 v76, v76, v174
	v_mul_f32_e32 v77, v77, v175
	v_mul_f32_e32 v78, v78, v176
	v_mul_f32_e32 v79, v79, v177
	ds_write2st64_b32 v81, v64, v65 offset0:16 offset1:17
	ds_write2st64_b32 v81, v66, v67 offset0:18 offset1:19
	ds_write2st64_b32 v81, v68, v69 offset0:20 offset1:21
	ds_write2st64_b32 v81, v70, v71 offset0:22 offset1:23
	ds_write2st64_b32 v81, v72, v73 offset0:24 offset1:25
	ds_write2st64_b32 v81, v74, v75 offset0:26 offset1:27
	ds_write2st64_b32 v81, v76, v77 offset0:28 offset1:29
	ds_write2st64_b32 v81, v78, v79 offset0:30 offset1:31
	v_mul_f32_e32 v80, v64, v64
	v_mul_f32_e32 v82, v65, v65
	v_fmac_f32_e32 v80, v66, v66
	v_fmac_f32_e32 v82, v67, v67
	v_fmac_f32_e32 v80, v68, v68
	v_fmac_f32_e32 v82, v69, v69
	v_fmac_f32_e32 v80, v70, v70
	v_fmac_f32_e32 v82, v71, v71
	v_fmac_f32_e32 v80, v72, v72
	v_fmac_f32_e32 v82, v73, v73
	v_fmac_f32_e32 v80, v74, v74
	v_fmac_f32_e32 v82, v75, v75
	v_fmac_f32_e32 v80, v76, v76
	v_fmac_f32_e32 v82, v77, v77
	v_fmac_f32_e32 v80, v78, v78
	v_fmac_f32_e32 v82, v79, v79
	v_add_f32_e32 v80, v80, v82
	ds_bpermute_b32 v82, v121, v80
	s_waitcnt lgkmcnt(0)
	v_add_f32_e32 v80, v80, v82
	ds_bpermute_b32 v82, v122, v80
	s_waitcnt lgkmcnt(0)
	v_add_f32_e32 v80, v80, v82
	s_and_saveexec_b64 s[8:9], s[6:7]
	ds_write_b32 v126, v80
	s_or_b64 exec, exec, s[8:9]
.Ll2_tail:
	s_add_i32 s11, s11, -1
	v_subrev_u32_e32 v126, 64, v126
	s_cmp_eq_u32 s12, 8
	s_mov_b32 s14, s12
	s_cbranch_scc0 .Ll2_step
	s_waitcnt vmcnt(0)

.LBB0_349:
	v_add_u32_e32 v192, s14, v212
	ds_read_b64_tr_b16 v[178:179], v192 offset:24576
	ds_read_b64_tr_b16 v[180:181], v192 offset:25088
	s_waitcnt lgkmcnt(9)
	v_mfma_f32_32x32x16_bf16 v[98:113], v[174:177], v[142:145], v[34:49]
	v_add_f32_e32 v82, v66, v67
	v_add_f32_e32 v82, v68, v82
	v_add_f32_e32 v82, v69, v82
	v_add_f32_e32 v82, v70, v82
	v_add_f32_e32 v82, v71, v82
	v_cvt_pk_bf16_f32 v138, v66, v67
	v_cvt_pk_bf16_f32 v139, v68, v69
	ds_read_b64_tr_b16 v[174:175], v192 offset:28672
	ds_read_b64_tr_b16 v[176:177], v192 offset:29184
	v_add_f32_e32 v66, v72, v82
	s_waitcnt lgkmcnt(10)
	v_mfma_f32_32x32x16_bf16 v[82:97], v[170:173], v[142:145], v[34:49]
	v_add_f32_e32 v66, v73, v66
	v_add_f32_e32 v66, v74, v66
	v_add_f32_e32 v118, v75, v66
	v_cvt_pk_bf16_f32 v140, v70, v71
	v_cvt_pk_bf16_f32 v141, v72, v73
	ds_read_b64_tr_b16 v[66:67], v192 offset:25600
	ds_read_b64_tr_b16 v[68:69], v192 offset:26112
	s_waitcnt lgkmcnt(11)
	v_mfma_f32_32x32x16_bf16 v[98:113], v[166:169], v[134:137], v[98:113]
	v_add_f32_e32 v70, v76, v118
	v_add_f32_e32 v70, v77, v70
	v_add_f32_e32 v70, v78, v70
	v_add_f32_e32 v118, v79, v70
	v_cvt_pk_bf16_f32 v130, v74, v75
	v_cvt_pk_bf16_f32 v131, v76, v77
	ds_read_b64_tr_b16 v[70:71], v192 offset:29696
	ds_read_b64_tr_b16 v[72:73], v192 offset:30208
	s_waitcnt lgkmcnt(12)
	v_mfma_f32_32x32x16_bf16 v[82:97], v[162:165], v[134:137], v[82:97]
	v_add_f32_e32 v74, v80, v118
	v_add_f32_e32 v74, v81, v74
	v_add_f32_e32 v74, v50, v74
	v_add_f32_e32 v118, v51, v74
	v_cvt_pk_bf16_f32 v132, v78, v79
	v_cvt_pk_bf16_f32 v133, v80, v81
	ds_read_b64_tr_b16 v[74:75], v192 offset:26624
	ds_read_b64_tr_b16 v[76:77], v192 offset:27136
	s_waitcnt lgkmcnt(13)
	v_mfma_f32_32x32x16_bf16 v[98:113], v[158:161], v[122:125], v[98:113]
	v_add_f32_e32 v78, v52, v118
	v_add_f32_e32 v78, v53, v78
	v_add_f32_e32 v78, v54, v78
	v_add_f32_e32 v78, v55, v78
	v_cvt_pk_bf16_f32 v126, v50, v51
	v_cvt_pk_bf16_f32 v127, v52, v53
	ds_read_b64_tr_b16 v[50:51], v192 offset:30720
	ds_read_b64_tr_b16 v[52:53], v192 offset:31232
	s_waitcnt lgkmcnt(14)
	v_mfma_f32_32x32x16_bf16 v[82:97], v[154:157], v[122:125], v[82:97]
	v_add_f32_e32 v78, v56, v78
	v_add_f32_e32 v78, v57, v78
	v_add_f32_e32 v78, v58, v78
	v_add_f32_e32 v78, v59, v78
	v_cvt_pk_bf16_f32 v128, v54, v55
	v_cvt_pk_bf16_f32 v129, v56, v57
	ds_read_b64_tr_b16 v[54:55], v192 offset:27648
	ds_read_b64_tr_b16 v[56:57], v192 offset:28160
	s_waitcnt lgkmcnt(14)
	v_mfma_f32_32x32x16_bf16 v[98:113], v[150:153], v[114:117], v[98:113]
	v_add_f32_e32 v78, v60, v78
	v_add_f32_e32 v78, v61, v78
	v_add_f32_e32 v78, v62, v78
	v_add_f32_e32 v78, v63, v78
	v_cvt_pk_bf16_f32 v118, v58, v59
	v_cvt_pk_bf16_f32 v119, v60, v61
	ds_read_b64_tr_b16 v[58:59], v192 offset:31744
	ds_read_b64_tr_b16 v[60:61], v192 offset:32256
	v_mfma_f32_32x32x16_bf16 v[82:97], v[146:149], v[114:117], v[82:97]
	v_add_f32_e32 v78, v64, v78
	v_add_f32_e32 v78, v65, v78
	v_add_f32_e32 v78, 0, v78
	v_cvt_pk_bf16_f32 v120, v62, v63
	v_cvt_pk_bf16_f32 v121, v64, v65
	v_lshl_add_u64 v[62:63], v[188:189], 0, s[62:63]
	s_add_i32 s14, s44, s43
	s_mov_b32 s15, m0
	s_mov_b32 m0, s14
	s_nop 0
	global_load_lds_dwordx4 v[62:63], off
	s_mov_b32 m0, s15
	v_lshl_add_u64 v[62:63], v[186:187], 0, s[62:63]
	s_add_i32 s14, s38, s48
	s_mov_b32 s15, m0
	s_mov_b32 m0, s14
	s_nop 0
	global_load_lds_dwordx4 v[62:63], off
	s_mov_b32 m0, s15
	v_max_f32_e32 v62, v98, v99
	v_max3_f32 v63, v100, v101, v83
	v_max3_f32 v62, v62, v82, v84
	v_max3_f32 v62, v62, v85, v102
	v_max3_f32 v63, v63, v104, v105
	v_max3_f32 v62, v62, v103, v86
	v_max3_f32 v63, v63, v88, v89
	v_max3_f32 v62, v62, v87, v106
	v_max3_f32 v63, v63, v108, v109
	v_max3_f32 v62, v62, v107, v90
	v_max3_f32 v63, v63, v92, v93
	v_max3_f32 v62, v62, v91, v110
	v_max3_f32 v63, v63, v112, v113
	v_max3_f32 v62, v62, v111, v94
	v_max3_f32 v63, v63, v96, v97
	v_max3_f32 v62, v62, v95, v63
	v_mov_b32_e32 v63, v62
	s_nop 1
	v_permlane32_swap_b32_e32 v62, v63
	v_max_f32_e32 v62, v62, v63
	v_cmp_lt_f32_e32 vcc, s73, v62
	s_cmp_lg_u64 vcc, 0
	v_add_f32_e32 v196, v214, v78
	s_cselect_b64 s[14:15], -1, 0
	s_cbranch_vccnz .LBB0_357
.LBB0_350:
	s_waitcnt lgkmcnt(14)
	v_mfma_f32_32x32x16_bf16 v[18:33], v[138:141], v[178:181], v[18:33]
	v_exp_f32_e32 v98, v98
	v_exp_f32_e32 v99, v99
	v_exp_f32_e32 v100, v100
	v_exp_f32_e32 v101, v101
	s_waitcnt lgkmcnt(12)
	v_mfma_f32_32x32x16_bf16 v[2:17], v[138:141], v[174:177], v[2:17]
	v_exp_f32_e32 v102, v102
	v_exp_f32_e32 v103, v103
	v_exp_f32_e32 v104, v104
	v_exp_f32_e32 v105, v105
	v_add_u32_e32 v78, s38, v211
	ds_read_b128 v[62:65], v78
	ds_read_b128 v[174:177], v78 offset:512
	s_waitcnt lgkmcnt(12)
	v_mfma_f32_32x32x16_bf16 v[18:33], v[130:133], v[66:69], v[18:33]
	v_exp_f32_e32 v106, v106
	v_exp_f32_e32 v107, v107
	v_exp_f32_e32 v108, v108
	v_exp_f32_e32 v109, v109
	ds_read_b128 v[178:181], v78 offset:2048
	ds_read_b128 v[170:173], v78 offset:2560
	s_waitcnt lgkmcnt(12)
	v_mfma_f32_32x32x16_bf16 v[2:17], v[130:133], v[70:73], v[2:17]
	v_exp_f32_e32 v110, v110
	v_exp_f32_e32 v111, v111
	v_exp_f32_e32 v112, v112
	v_exp_f32_e32 v113, v113
	ds_read_b128 v[166:169], v78 offset:4096
	ds_read_b128 v[162:165], v78 offset:4608
	s_waitcnt lgkmcnt(12)
	v_mfma_f32_32x32x16_bf16 v[18:33], v[126:129], v[74:77], v[18:33]
	v_exp_f32_e32 v82, v82
	v_exp_f32_e32 v83, v83
	v_exp_f32_e32 v84, v84
	v_exp_f32_e32 v85, v85
	ds_read_b128 v[158:161], v78 offset:6144
	ds_read_b128 v[154:157], v78 offset:6656
	s_waitcnt lgkmcnt(12)
	v_mfma_f32_32x32x16_bf16 v[2:17], v[126:129], v[50:53], v[2:17]
	v_exp_f32_e32 v86, v86
	v_exp_f32_e32 v87, v87
	v_exp_f32_e32 v88, v88
	v_exp_f32_e32 v89, v89
	s_waitcnt lgkmcnt(10)
	v_mfma_f32_32x32x16_bf16 v[18:33], v[118:121], v[54:57], v[18:33]
	v_exp_f32_e32 v90, v90
	v_exp_f32_e32 v91, v91
	v_exp_f32_e32 v92, v92
	v_exp_f32_e32 v93, v93
	s_waitcnt lgkmcnt(8)
	v_mfma_f32_32x32x16_bf16 v[2:17], v[118:121], v[58:61], v[2:17]
	v_exp_f32_e32 v94, v94
	v_exp_f32_e32 v95, v95
	v_exp_f32_e32 v96, v96
	v_exp_f32_e32 v97, v97
	s_waitcnt vmcnt(2) lgkmcnt(0)
	s_barrier
	s_andn2_b64 vcc, exec, s[14:15]
	s_cbranch_vccnz .LBB0_352
	s_waitcnt lgkmcnt(0)
	v_add_u32_e32 v50, s3, v213
	v_add_u32_e32 v197, 0xc000, v50
	v_add_u32_e32 v198, 0xc008, v50
	v_add_u32_e32 v199, 0xc020, v50
	v_add_u32_e32 v215, 0xc028, v50
	v_add_u32_e32 v216, 0xc040, v50
	v_add_u32_e32 v217, 0xc048, v50
	v_add_u32_e32 v218, 0xc060, v50
	v_add_u32_e32 v219, 0xc068, v50
	ds_read2_b32 v[50:51], v216 offset1:1
	ds_read2_b32 v[52:53], v217 offset1:1
	ds_read2_b32 v[54:55], v218 offset1:1
	ds_read2_b32 v[56:57], v219 offset1:1
	ds_read2_b32 v[58:59], v197 offset1:1
	ds_read2_b32 v[60:61], v198 offset1:1
	ds_read2_b32 v[66:67], v199 offset1:1
	ds_read2_b32 v[68:69], v215 offset1:1
	s_waitcnt lgkmcnt(4)
	v_pk_mul_f32 v[32:33], v[32:33], v[56:57]
	v_pk_mul_f32 v[30:31], v[30:31], v[54:55]
	v_pk_mul_f32 v[28:29], v[28:29], v[52:53]
	v_pk_mul_f32 v[26:27], v[26:27], v[50:51]
	s_waitcnt lgkmcnt(0)
	v_pk_mul_f32 v[24:25], v[24:25], v[68:69]
	v_pk_mul_f32 v[22:23], v[22:23], v[66:67]
	v_pk_mul_f32 v[20:21], v[20:21], v[60:61]
	v_pk_mul_f32 v[18:19], v[18:19], v[58:59]
	v_pk_mul_f32 v[16:17], v[16:17], v[56:57]
	v_pk_mul_f32 v[14:15], v[14:15], v[54:55]
	v_pk_mul_f32 v[12:13], v[12:13], v[52:53]
	v_pk_mul_f32 v[10:11], v[10:11], v[50:51]
	v_pk_mul_f32 v[8:9], v[8:9], v[68:69]
	v_pk_mul_f32 v[6:7], v[6:7], v[66:67]
	v_pk_mul_f32 v[4:5], v[4:5], v[60:61]
	v_pk_mul_f32 v[2:3], v[2:3], v[58:59]
.LBB0_352:
	s_add_i32 s14, s38, 0x2000
	s_cmpk_lg_i32 s38, 0x4000
	s_cselect_b32 s49, s14, 0
	v_add_u32_e32 v192, s44, v212
	ds_read_b64_tr_b16 v[150:151], v192 offset:24576
	ds_read_b64_tr_b16 v[152:153], v192 offset:25088
	s_waitcnt lgkmcnt(9)
	v_mfma_f32_32x32x16_bf16 v[66:81], v[62:65], v[142:145], v[34:49]
	v_add_f32_e32 v50, v98, v99
	v_add_f32_e32 v50, v100, v50
	v_add_f32_e32 v50, v101, v50
	v_add_f32_e32 v50, v102, v50
	v_add_f32_e32 v50, v103, v50
	v_cvt_pk_bf16_f32 v138, v98, v99
	v_cvt_pk_bf16_f32 v139, v100, v101
	ds_read_b64_tr_b16 v[146:147], v192 offset:28672
	ds_read_b64_tr_b16 v[148:149], v192 offset:29184
	v_add_f32_e32 v50, v104, v50
	v_add_f32_e32 v50, v105, v50
	v_add_f32_e32 v50, v106, v50
	v_add_f32_e32 v118, v107, v50
	s_waitcnt lgkmcnt(10)
	v_mfma_f32_32x32x16_bf16 v[50:65], v[174:177], v[142:145], v[34:49]
	v_cvt_pk_bf16_f32 v140, v102, v103
	v_cvt_pk_bf16_f32 v141, v104, v105
	ds_read_b64_tr_b16 v[98:99], v192 offset:25600
	ds_read_b64_tr_b16 v[100:101], v192 offset:26112
	s_waitcnt lgkmcnt(11)
	v_mfma_f32_32x32x16_bf16 v[66:81], v[178:181], v[134:137], v[66:81]
	v_add_f32_e32 v102, v108, v118
	v_add_f32_e32 v102, v109, v102
	v_add_f32_e32 v102, v110, v102
	v_add_f32_e32 v118, v111, v102
	v_cvt_pk_bf16_f32 v130, v106, v107
	v_cvt_pk_bf16_f32 v131, v108, v109
	ds_read_b64_tr_b16 v[102:103], v192 offset:29696
	ds_read_b64_tr_b16 v[104:105], v192 offset:30208
	s_waitcnt lgkmcnt(12)
	v_mfma_f32_32x32x16_bf16 v[50:65], v[170:173], v[134:137], v[50:65]
	v_add_f32_e32 v106, v112, v118
	v_add_f32_e32 v106, v113, v106
	v_add_f32_e32 v106, v82, v106
	v_add_f32_e32 v118, v83, v106
	v_cvt_pk_bf16_f32 v132, v110, v111
	v_cvt_pk_bf16_f32 v133, v112, v113
	ds_read_b64_tr_b16 v[106:107], v192 offset:26624
	ds_read_b64_tr_b16 v[108:109], v192 offset:27136
	s_waitcnt lgkmcnt(13)
	v_mfma_f32_32x32x16_bf16 v[66:81], v[166:169], v[122:125], v[66:81]
	v_add_f32_e32 v110, v84, v118
	v_add_f32_e32 v110, v85, v110
	v_add_f32_e32 v110, v86, v110
	v_add_f32_e32 v110, v87, v110
	v_cvt_pk_bf16_f32 v126, v82, v83
	v_cvt_pk_bf16_f32 v127, v84, v85
	ds_read_b64_tr_b16 v[82:83], v192 offset:30720
	ds_read_b64_tr_b16 v[84:85], v192 offset:31232
	s_waitcnt lgkmcnt(14)
	v_mfma_f32_32x32x16_bf16 v[50:65], v[162:165], v[122:125], v[50:65]
	v_add_f32_e32 v110, v88, v110
	v_add_f32_e32 v110, v89, v110
	v_add_f32_e32 v110, v90, v110
	v_add_f32_e32 v110, v91, v110
	v_cvt_pk_bf16_f32 v128, v86, v87
	v_cvt_pk_bf16_f32 v129, v88, v89
	ds_read_b64_tr_b16 v[86:87], v192 offset:27648
	ds_read_b64_tr_b16 v[88:89], v192 offset:28160
	s_waitcnt lgkmcnt(14)
	v_mfma_f32_32x32x16_bf16 v[66:81], v[158:161], v[114:117], v[66:81]
	v_add_f32_e32 v110, v92, v110
	v_add_f32_e32 v110, v93, v110
	v_add_f32_e32 v110, v94, v110
	v_add_f32_e32 v110, v95, v110
	v_cvt_pk_bf16_f32 v118, v90, v91
	v_cvt_pk_bf16_f32 v119, v92, v93
	ds_read_b64_tr_b16 v[90:91], v192 offset:31744
	ds_read_b64_tr_b16 v[92:93], v192 offset:32256
	v_mfma_f32_32x32x16_bf16 v[50:65], v[154:157], v[114:117], v[50:65]
	v_add_f32_e32 v110, v96, v110
	v_add_f32_e32 v110, v97, v110
	v_add_f32_e32 v110, 0, v110
	v_cvt_pk_bf16_f32 v120, v94, v95
	v_cvt_pk_bf16_f32 v121, v96, v97
	v_max_f32_e32 v94, v66, v67
	s_nop 5
	v_max3_f32 v95, v68, v69, v51
	v_max3_f32 v94, v94, v50, v52
	v_max3_f32 v94, v94, v53, v70
	v_max3_f32 v95, v95, v72, v73
	v_max3_f32 v94, v94, v71, v54
	v_max3_f32 v95, v95, v56, v57
	v_max3_f32 v94, v94, v55, v74
	v_max3_f32 v95, v95, v76, v77
	v_max3_f32 v94, v94, v75, v58
	v_max3_f32 v95, v95, v60, v61
	v_max3_f32 v94, v94, v59, v78
	v_max3_f32 v95, v95, v80, v81
	v_max3_f32 v94, v94, v79, v62
	v_max3_f32 v95, v95, v64, v65
	v_max3_f32 v94, v94, v63, v95
	v_mov_b32_e32 v95, v94
	s_nop 1
	v_permlane32_swap_b32_e32 v94, v95
	s_add_i32 s14, s38, s43
	s_mov_b32 s15, m0
	s_mov_b32 m0, s14
	s_nop 0
	global_load_lds_dwordx4 v[188:189], off
	s_mov_b32 m0, s15
	v_max_f32_e32 v94, v94, v95
	s_add_i32 s14, s49, s48
	s_mov_b32 s15, m0
	s_mov_b32 m0, s14
	s_nop 0
	global_load_lds_dwordx4 v[186:187], off
	s_mov_b32 m0, s15
	v_cmp_lt_f32_e32 vcc, s73, v94
	s_cmp_lg_u64 vcc, 0
	v_add_f32_e32 v214, v196, v110
	s_cselect_b64 s[14:15], -1, 0
	s_cbranch_vccnz .LBB0_360
.LBB0_353:
	s_waitcnt lgkmcnt(14)
	v_mfma_f32_32x32x16_bf16 v[18:33], v[138:141], v[150:153], v[18:33]
	v_exp_f32_e32 v66, v66
	v_exp_f32_e32 v67, v67
	v_exp_f32_e32 v68, v68
	v_exp_f32_e32 v69, v69
	s_waitcnt lgkmcnt(12)
	v_mfma_f32_32x32x16_bf16 v[2:17], v[138:141], v[146:149], v[2:17]
	v_exp_f32_e32 v70, v70
	v_exp_f32_e32 v71, v71
	v_exp_f32_e32 v72, v72
	v_exp_f32_e32 v73, v73
	v_add_u32_e32 v94, s49, v211
	ds_read_b128 v[174:177], v94
	ds_read_b128 v[170:173], v94 offset:512
	s_waitcnt lgkmcnt(12)
	v_mfma_f32_32x32x16_bf16 v[18:33], v[130:133], v[98:101], v[18:33]
	v_exp_f32_e32 v74, v74
	v_exp_f32_e32 v75, v75
	v_exp_f32_e32 v76, v76
	v_exp_f32_e32 v77, v77
	ds_read_b128 v[166:169], v94 offset:2048
	ds_read_b128 v[162:165], v94 offset:2560
	s_waitcnt lgkmcnt(12)
	v_mfma_f32_32x32x16_bf16 v[2:17], v[130:133], v[102:105], v[2:17]
	v_exp_f32_e32 v78, v78
	v_exp_f32_e32 v79, v79
	v_exp_f32_e32 v80, v80
	v_exp_f32_e32 v81, v81
	ds_read_b128 v[158:161], v94 offset:4096
	ds_read_b128 v[154:157], v94 offset:4608
	s_waitcnt lgkmcnt(12)
	v_mfma_f32_32x32x16_bf16 v[18:33], v[126:129], v[106:109], v[18:33]
	v_exp_f32_e32 v50, v50
	v_exp_f32_e32 v51, v51
	v_exp_f32_e32 v52, v52
	v_exp_f32_e32 v53, v53
	ds_read_b128 v[150:153], v94 offset:6144
	ds_read_b128 v[146:149], v94 offset:6656
	s_waitcnt lgkmcnt(12)
	v_mfma_f32_32x32x16_bf16 v[2:17], v[126:129], v[82:85], v[2:17]
	v_exp_f32_e32 v54, v54
	v_exp_f32_e32 v55, v55
	v_exp_f32_e32 v56, v56
	v_exp_f32_e32 v57, v57
	s_waitcnt lgkmcnt(10)
	v_mfma_f32_32x32x16_bf16 v[18:33], v[118:121], v[86:89], v[18:33]
	v_exp_f32_e32 v58, v58
	v_exp_f32_e32 v59, v59
	v_exp_f32_e32 v60, v60
	v_exp_f32_e32 v61, v61
	s_waitcnt lgkmcnt(8)
	v_mfma_f32_32x32x16_bf16 v[2:17], v[118:121], v[90:93], v[2:17]
	v_exp_f32_e32 v62, v62
	v_exp_f32_e32 v63, v63
	v_exp_f32_e32 v64, v64
	v_exp_f32_e32 v65, v65
	s_waitcnt vmcnt(2) lgkmcnt(0)
	s_barrier
	s_andn2_b64 vcc, exec, s[14:15]
	s_cbranch_vccnz .LBB0_355
	s_waitcnt lgkmcnt(0)
	v_add_u32_e32 v82, s3, v213
	v_add_u32_e32 v197, 0xc000, v82
	v_add_u32_e32 v198, 0xc008, v82
	v_add_u32_e32 v199, 0xc020, v82
	v_add_u32_e32 v215, 0xc028, v82
	v_add_u32_e32 v216, 0xc040, v82
	v_add_u32_e32 v217, 0xc048, v82
	v_add_u32_e32 v218, 0xc060, v82
	v_add_u32_e32 v219, 0xc068, v82
	ds_read2_b32 v[82:83], v216 offset1:1
	ds_read2_b32 v[84:85], v217 offset1:1
	ds_read2_b32 v[86:87], v218 offset1:1
	ds_read2_b32 v[88:89], v219 offset1:1
	ds_read2_b32 v[90:91], v197 offset1:1
	ds_read2_b32 v[92:93], v198 offset1:1
	ds_read2_b32 v[94:95], v199 offset1:1
	ds_read2_b32 v[96:97], v215 offset1:1
	s_waitcnt lgkmcnt(4)
	v_pk_mul_f32 v[32:33], v[32:33], v[88:89]
	v_pk_mul_f32 v[30:31], v[30:31], v[86:87]
	v_pk_mul_f32 v[28:29], v[28:29], v[84:85]
	v_pk_mul_f32 v[26:27], v[26:27], v[82:83]
	s_waitcnt lgkmcnt(0)
	v_pk_mul_f32 v[24:25], v[24:25], v[96:97]
	v_pk_mul_f32 v[22:23], v[22:23], v[94:95]
	v_pk_mul_f32 v[20:21], v[20:21], v[92:93]
	v_pk_mul_f32 v[18:19], v[18:19], v[90:91]
	v_pk_mul_f32 v[16:17], v[16:17], v[88:89]
	v_pk_mul_f32 v[14:15], v[14:15], v[86:87]
	v_pk_mul_f32 v[12:13], v[12:13], v[84:85]
	v_pk_mul_f32 v[10:11], v[10:11], v[82:83]
	v_pk_mul_f32 v[8:9], v[8:9], v[96:97]
	v_pk_mul_f32 v[6:7], v[6:7], v[94:95]
	v_pk_mul_f32 v[4:5], v[4:5], v[92:93]
	v_pk_mul_f32 v[2:3], v[2:3], v[90:91]
